# strategy 8: NSA sel/window S blocks - QK accumulate chains moved to a free quad so the next K fragment loads issue right behind the MFMAs (hazard nops gone)
# speedup vs baseline: 1.0084x; 1.0013x over previous
; DI float ex2(float x) { return __builtin_amdgcn_exp2f(x); }
; #define SB0 __builtin_amdgcn_sched_barrier(0)
; DI void nsa_S(f32x4 (&s)[4], const char* Kb, const char* Vb, const bf16x8 (&qf)[4], bf16x8 (&v0)[4], int lr, int quad) {
;   bf16x8 k0[4], k1[4], k2[4], k3[4];
;   ldk4(k0, Kb, 0, lr, quad); SB0;
;   ldk4(k1, Kb, 1, lr, quad); s[0] = mma4(k0, qf); SB0;
;   ldk4(k2, Kb, 2, lr, quad); s[1] = mma4(k1, qf); SB0;
;   ldk4(k3, Kb, 3, lr, quad); s[2] = mma4(k2, qf); SB0;
;   ldv4(v0, Vb, 0, lr, quad); s[3] = mma4(k3, qf); SB0;
; }
; template <bool MASKED, class MF>
; DI void flash_update(f32x4 (&s)[4], float scl, float& mx, float& ls, f32x4 (&o)[8], MF maskfn, bool lane_on) {
;   float tmax = -1e30f;
; #pragma unroll
;   for (int kt = 0; kt < 4; ++kt)
; #pragma unroll
;     for (int i = 0; i < 4; ++i) {
;       if (MASKED) { if (maskfn(kt, i)) s[kt][i] = -1e30f; }
;       tmax = fmaxf(tmax, s[kt][i]);
;     }
;   tmax = rowmax4(tmax);
;   if (!lane_on) tmax = -1e30f;
;   const float th = 8.f / scl;
;   if (__any(tmax > mx + th)) {
;     const float mnew = fmaxf(mx, tmax);
;     const float alpha = ex2((mx - mnew) * scl);
;     ls *= alpha;
; #pragma unroll
;     for (int dt = 0; dt < 8; ++dt) o[dt] *= alpha;
;     mx = mnew;
;   }
.LBB0_817:
	s_or_b32 s59, s48, s56
	s_cmp_gt_u32 s59, s2
	s_cbranch_scc1 .LBB0_816
	s_and_b32 s38, s59, 31
	s_waitcnt lgkmcnt(0)
	v_mov_b32_e32 v0, v172
	v_lshrrev_b32_e32 v1, s59, v0
	v_bfe_u32 v0, v0, s38, 1
	v_and_b32_e32 v1, 1, v1
	v_cmp_ne_u32_e32 vcc, 0, v0
	v_cmp_eq_u32_e64 s[38:39], 1, v1
	s_cbranch_vccz .LBB0_829
	s_lshl_b32 s48, s48, 15
	s_add_i32 s58, s57, s48
	v_add_u32_e32 v8, s58, v234
	v_add_u32_e32 v122, v8, v235
	v_add_u32_e32 v124, v8, v237
	v_add_u32_e32 v123, v8, v236
	ds_read_b128 v[0:3], v122
	ds_read_b128 v[4:7], v123
	v_add_u32_e32 v125, v8, v238
	ds_read_b128 v[8:11], v124
	ds_read_b128 v[12:15], v125
	ds_read_b128 v[98:101], v122 offset:4096
	ds_read_b128 v[102:105], v123 offset:4096
	ds_read_b128 v[106:109], v124 offset:4096
	ds_read_b128 v[110:113], v125 offset:4096
	s_waitcnt lgkmcnt(7)
	v_mfma_f32_16x16x32_bf16 v[142:145], v[0:3], v[18:21], 0
	s_waitcnt lgkmcnt(6)
	v_mfma_f32_16x16x32_bf16 v[142:145], v[4:7], v[22:25], v[142:145]
	s_waitcnt lgkmcnt(5)
	v_mfma_f32_16x16x32_bf16 v[142:145], v[8:11], v[26:29], v[142:145]
	s_waitcnt lgkmcnt(4)
	v_mfma_f32_16x16x32_bf16 v[114:117], v[12:15], v[30:33], v[142:145]
	ds_read_b128 v[0:3], v122 offset:8192
	ds_read_b128 v[4:7], v123 offset:8192
	ds_read_b128 v[8:11], v124 offset:8192
	ds_read_b128 v[12:15], v125 offset:8192
	s_waitcnt lgkmcnt(7)
	v_mfma_f32_16x16x32_bf16 v[98:101], v[98:101], v[18:21], 0
	s_waitcnt lgkmcnt(6)
	v_mfma_f32_16x16x32_bf16 v[98:101], v[102:105], v[22:25], v[98:101]
	s_waitcnt lgkmcnt(5)
	v_mfma_f32_16x16x32_bf16 v[98:101], v[106:109], v[26:29], v[98:101]
	s_waitcnt lgkmcnt(4)
	v_mfma_f32_16x16x32_bf16 v[118:121], v[110:113], v[30:33], v[98:101]
	s_nop 0
	ds_read_b128 v[126:129], v122 offset:12288
	ds_read_b128 v[130:133], v123 offset:12288
	ds_read_b128 v[134:137], v124 offset:12288
	ds_read_b128 v[138:141], v125 offset:12288
	s_waitcnt lgkmcnt(7)
	v_mfma_f32_16x16x32_bf16 v[142:145], v[0:3], v[18:21], 0
	s_waitcnt lgkmcnt(6)
	v_mfma_f32_16x16x32_bf16 v[142:145], v[4:7], v[22:25], v[142:145]
	s_waitcnt lgkmcnt(5)
	v_mfma_f32_16x16x32_bf16 v[142:145], v[8:11], v[26:29], v[142:145]
	s_waitcnt lgkmcnt(4)
	v_mfma_f32_16x16x32_bf16 v[122:125], v[12:15], v[30:33], v[142:145]
	v_add_u32_e32 v0, s58, v242
	v_add_u32_e32 v174, v0, v241
	ds_read_b128 v[98:101], v174 offset:16384
	ds_read_b128 v[102:105], v174 offset:18432
	ds_read_b128 v[106:109], v174 offset:20480
	ds_read_b128 v[110:113], v174 offset:22528
	s_waitcnt lgkmcnt(7)
	v_mfma_f32_16x16x32_bf16 v[0:3], v[126:129], v[18:21], 0
	s_waitcnt lgkmcnt(6)
	v_mfma_f32_16x16x32_bf16 v[0:3], v[130:133], v[22:25], v[0:3]
	s_waitcnt lgkmcnt(5)
	v_mfma_f32_16x16x32_bf16 v[0:3], v[134:137], v[26:29], v[0:3]
	s_waitcnt lgkmcnt(4)
	v_mfma_f32_16x16x32_bf16 v[126:129], v[138:141], v[30:33], v[0:3]
	s_nop 0
	s_mov_b64 s[48:49], -1
	s_cmp_lg_u32 s59, s2
	v_add_f32_e32 v176, 0x427af232, v173
	s_cbranch_scc0 .LBB0_823
	s_nop 1
	v_max3_f32 v0, v114, s41, v115
	v_max3_f32 v0, v0, v116, v117
	v_max3_f32 v0, v0, v118, v119
	v_max3_f32 v0, v0, v120, v121
	v_max3_f32 v0, v0, v122, v123
	v_max3_f32 v0, v0, v124, v125
	v_max3_f32 v0, v0, v126, v127
	v_max3_f32 v0, v0, v128, v129
	v_mov_b32_e32 v1, v0
	s_nop 1
	v_permlane16_swap_b32_e32 v0, v1
	v_max_f32_e32 v1, v1, v1
	v_max_f32_e32 v0, v0, v0
	v_max_f32_e32 v0, v0, v1
	v_mov_b32_e32 v1, v0
	s_nop 1
	v_permlane32_swap_b32_e32 v0, v1
	v_max_f32_e32 v1, v1, v1
	v_max_f32_e32 v0, v0, v0
	v_max_f32_e32 v0, v0, v1
	v_cndmask_b32_e64 v0, v231, v0, s[38:39]
	v_mov_b64_e32 v[160:161], v[68:69]
	v_mov_b64_e32 v[156:157], v[72:73]
	v_mov_b64_e32 v[152:153], v[76:77]
	v_mov_b64_e32 v[148:149], v[80:81]
	v_mov_b64_e32 v[144:145], v[84:85]
	v_mov_b64_e32 v[140:141], v[88:89]
	v_mov_b64_e32 v[136:137], v[92:93]
	v_mov_b64_e32 v[132:133], v[96:97]
	v_cmp_gt_f32_e32 vcc, v0, v176
	v_mov_b64_e32 v[158:159], v[66:67]
	v_mov_b64_e32 v[154:155], v[70:71]
	v_mov_b64_e32 v[150:151], v[74:75]
	v_mov_b64_e32 v[146:147], v[78:79]
	v_mov_b64_e32 v[142:143], v[82:83]
	v_mov_b64_e32 v[138:139], v[86:87]
	v_mov_b64_e32 v[134:135], v[90:91]
	v_mov_b64_e32 v[130:131], v[94:95]
	v_mov_b32_e32 v177, v170
	v_mov_b32_e32 v175, v173
	s_cbranch_vccz .LBB0_822
	v_max_f32_e32 v0, v0, v0
	v_max_f32_e32 v1, v173, v173
	v_max_f32_e32 v175, v1, v0
	v_sub_f32_e32 v0, v173, v175
	v_mul_f32_e32 v0, 0x3e0293ee, v0
	v_exp_f32_e32 v0, v0
	s_nop 0
	v_mul_f32_e32 v177, v170, v0
	v_pk_mul_f32 v[132:133], v[96:97], v[0:1] op_sel_hi:[1,0]
	v_pk_mul_f32 v[130:131], v[94:95], v[0:1] op_sel_hi:[1,0]
	v_pk_mul_f32 v[136:137], v[92:93], v[0:1] op_sel_hi:[1,0]
	v_pk_mul_f32 v[134:135], v[90:91], v[0:1] op_sel_hi:[1,0]
	v_pk_mul_f32 v[140:141], v[88:89], v[0:1] op_sel_hi:[1,0]
	v_pk_mul_f32 v[138:139], v[86:87], v[0:1] op_sel_hi:[1,0]
	v_pk_mul_f32 v[144:145], v[84:85], v[0:1] op_sel_hi:[1,0]
	v_pk_mul_f32 v[142:143], v[82:83], v[0:1] op_sel_hi:[1,0]
	v_pk_mul_f32 v[148:149], v[80:81], v[0:1] op_sel_hi:[1,0]
	v_pk_mul_f32 v[146:147], v[78:79], v[0:1] op_sel_hi:[1,0]
	v_pk_mul_f32 v[152:153], v[76:77], v[0:1] op_sel_hi:[1,0]
	v_pk_mul_f32 v[150:151], v[74:75], v[0:1] op_sel_hi:[1,0]
	v_pk_mul_f32 v[156:157], v[72:73], v[0:1] op_sel_hi:[1,0]
	v_pk_mul_f32 v[154:155], v[70:71], v[0:1] op_sel_hi:[1,0]
	v_pk_mul_f32 v[160:161], v[68:69], v[0:1] op_sel_hi:[1,0]
	v_pk_mul_f32 v[158:159], v[66:67], v[0:1] op_sel_hi:[1,0]

; #define SB0 __builtin_amdgcn_sched_barrier(0)
; DI void nsa_S(f32x4 (&s)[4], const char* Kb, const char* Vb, const bf16x8 (&qf)[4], bf16x8 (&v0)[4], int lr, int quad) {
;   bf16x8 k0[4], k1[4], k2[4], k3[4];
;   ldk4(k0, Kb, 0, lr, quad); SB0;
;   ldk4(k1, Kb, 1, lr, quad); s[0] = mma4(k0, qf); SB0;
;   ldk4(k2, Kb, 2, lr, quad); s[1] = mma4(k1, qf); SB0;
;   ldk4(k3, Kb, 3, lr, quad); s[2] = mma4(k2, qf); SB0;
;   ldv4(v0, Vb, 0, lr, quad); s[3] = mma4(k3, qf); SB0;
; }
; DI void nsa_item(const Params& p, int b, int g, int qb, char* smem, int tid) {
;     ...
;       auto mf = [&](int kt, int i) __attribute__((always_inline)) {
;         int key = j * 64 + kt * 16 + quad * 4 + i;
;         return (key > qp) || (key <= qp - 512);
;       };
;       if (j * 64 + 63 <= q0 && j * 64 > q0 + 31 - 512) flash_update<false>(s, SCL, mx2, l2, o, mf, true);
;       else flash_update<true>(s, SCL, mx2, l2, o, mf, true);
.LBB0_844:
	s_lshl_b32 s5, s6, 15
	s_add_i32 s24, s23, s5
	v_add_u32_e32 v8, s24, v234
	v_add_u32_e32 v146, v8, v235
	v_add_u32_e32 v151, v8, v237
	v_add_u32_e32 v150, v8, v236
	ds_read_b128 v[0:3], v146
	ds_read_b128 v[4:7], v150
	v_add_u32_e32 v152, v8, v238
	ds_read_b128 v[8:11], v151
	ds_read_b128 v[12:15], v152
	ds_read_b128 v[130:133], v146 offset:4096
	ds_read_b128 v[134:137], v150 offset:4096
	ds_read_b128 v[138:141], v151 offset:4096
	ds_read_b128 v[142:145], v152 offset:4096
	s_waitcnt lgkmcnt(7)
	v_mfma_f32_16x16x32_bf16 v[174:177], v[0:3], v[18:21], 0
	s_waitcnt lgkmcnt(6)
	v_mfma_f32_16x16x32_bf16 v[174:177], v[4:7], v[22:25], v[174:177]
	s_waitcnt lgkmcnt(5)
	v_mfma_f32_16x16x32_bf16 v[174:177], v[8:11], v[26:29], v[174:177]
	s_waitcnt lgkmcnt(4)
	v_mfma_f32_16x16x32_bf16 v[158:161], v[12:15], v[30:33], v[174:177]
	ds_read_b128 v[0:3], v146 offset:8192
	ds_read_b128 v[4:7], v150 offset:8192
	ds_read_b128 v[8:11], v151 offset:8192
	ds_read_b128 v[12:15], v152 offset:8192
	s_waitcnt lgkmcnt(7)
	v_mfma_f32_16x16x32_bf16 v[130:133], v[130:133], v[18:21], 0
	s_waitcnt lgkmcnt(6)
	v_mfma_f32_16x16x32_bf16 v[130:133], v[134:137], v[22:25], v[130:133]
	s_waitcnt lgkmcnt(5)
	v_mfma_f32_16x16x32_bf16 v[130:133], v[138:141], v[26:29], v[130:133]
	s_waitcnt lgkmcnt(4)
	v_mfma_f32_16x16x32_bf16 v[154:157], v[142:145], v[30:33], v[130:133]
	s_nop 0
	ds_read_b128 v[146:149], v146 offset:12288
	ds_read_b128 v[162:165], v150 offset:12288
	ds_read_b128 v[166:169], v151 offset:12288
	ds_read_b128 v[170:173], v152 offset:12288
	s_waitcnt lgkmcnt(7)
	v_mfma_f32_16x16x32_bf16 v[174:177], v[0:3], v[18:21], 0
	s_waitcnt lgkmcnt(6)
	v_mfma_f32_16x16x32_bf16 v[174:177], v[4:7], v[22:25], v[174:177]
	s_waitcnt lgkmcnt(5)
	v_mfma_f32_16x16x32_bf16 v[174:177], v[8:11], v[26:29], v[174:177]
	s_waitcnt lgkmcnt(4)
	v_mfma_f32_16x16x32_bf16 v[150:153], v[12:15], v[30:33], v[174:177]
	v_add_u32_e32 v0, s24, v242
	v_add_u32_e32 v247, v0, v241
	ds_read_b128 v[130:133], v247 offset:16384
	ds_read_b128 v[134:137], v247 offset:18432
	ds_read_b128 v[138:141], v247 offset:20480
	ds_read_b128 v[142:145], v247 offset:22528
	s_waitcnt lgkmcnt(7)
	v_mfma_f32_16x16x32_bf16 v[0:3], v[146:149], v[18:21], 0
	s_waitcnt lgkmcnt(6)
	v_mfma_f32_16x16x32_bf16 v[0:3], v[162:165], v[22:25], v[0:3]
	s_waitcnt lgkmcnt(5)
	v_mfma_f32_16x16x32_bf16 v[0:3], v[166:169], v[26:29], v[0:3]
	s_waitcnt lgkmcnt(4)
	v_mfma_f32_16x16x32_bf16 v[146:149], v[170:173], v[30:33], v[0:3]
	s_nop 0
	s_lshl_b32 s6, s4, 6
	s_or_b32 s4, s6, 63
	s_cmp_le_u32 s4, s85
	s_cselect_b64 s[4:5], -1, 0
	s_cmp_gt_i32 s6, s21
	s_cselect_b64 s[8:9], -1, 0
	s_and_b64 s[8:9], s[4:5], s[8:9]
	s_mov_b64 s[4:5], -1
	s_andn2_b64 vcc, exec, s[8:9]
	v_add_f32_e32 v249, 0x427af232, v246
	s_cbranch_vccz .LBB0_849
; DI float ex2(float x) { return __builtin_amdgcn_exp2f(x); }
; template <bool MASKED, class MF>
; DI void flash_update(f32x4 (&s)[4], float scl, float& mx, float& ls, f32x4 (&o)[8], MF maskfn, bool lane_on) {
;   float tmax = -1e30f;
; #pragma unroll
;   for (int kt = 0; kt < 4; ++kt)
; #pragma unroll
;     for (int i = 0; i < 4; ++i) {
;       if (MASKED) { if (maskfn(kt, i)) s[kt][i] = -1e30f; }
;       tmax = fmaxf(tmax, s[kt][i]);
;     }
;   tmax = rowmax4(tmax);
;   if (!lane_on) tmax = -1e30f;
;   const float th = 8.f / scl;
;   if (__any(tmax > mx + th)) {
;     const float mnew = fmaxf(mx, tmax);
;     const float alpha = ex2((mx - mnew) * scl);
;     ls *= alpha;
; #pragma unroll
;     for (int dt = 0; dt < 8; ++dt) o[dt] *= alpha;
;     mx = mnew;
;   }
	v_or_b32_e32 v15, s6, v214
	v_cmp_gt_i32_e32 vcc, v15, v233
	v_cmp_le_i32_e64 s[4:5], v15, v245
	s_or_b64 vcc, vcc, s[4:5]
	v_cndmask_b32_e32 v0, v158, v231, vcc
	v_cmp_ge_i32_e32 vcc, v15, v233
	v_cmp_lt_i32_e64 s[4:5], v15, v245
	s_or_b64 vcc, vcc, s[4:5]
	v_or_b32_e32 v2, 2, v15
	v_cndmask_b32_e32 v1, v159, v231, vcc
	v_cmp_gt_i32_e32 vcc, v2, v233
	v_cmp_le_i32_e64 s[4:5], v2, v245
	s_or_b64 vcc, vcc, s[4:5]
	v_or_b32_e32 v3, 3, v15
	v_cndmask_b32_e32 v2, v160, v231, vcc
	v_cmp_gt_i32_e32 vcc, v3, v233
	v_cmp_le_i32_e64 s[4:5], v3, v245
	s_or_b64 s[4:5], vcc, s[4:5]
	v_max3_f32 v4, v0, s41, v1
	v_cndmask_b32_e64 v3, v161, v231, s[4:5]
	v_max3_f32 v6, v4, v2, v3
	v_or_b32_e32 v4, 16, v15
	v_cmp_gt_i32_e32 vcc, v4, v233
	v_cmp_le_i32_e64 s[6:7], v4, v245
	s_or_b64 vcc, vcc, s[6:7]
	v_or_b32_e32 v5, 17, v15
	v_cndmask_b32_e32 v4, v154, v231, vcc
	v_cmp_gt_i32_e32 vcc, v5, v233
	v_cmp_le_i32_e64 s[6:7], v5, v245
	s_or_b64 vcc, vcc, s[6:7]
	v_cndmask_b32_e32 v5, v155, v231, vcc
	v_max3_f32 v8, v6, v4, v5
	v_or_b32_e32 v6, 18, v15
	v_cmp_gt_i32_e32 vcc, v6, v233
	v_cmp_le_i32_e64 s[6:7], v6, v245
	s_or_b64 vcc, vcc, s[6:7]
	v_or_b32_e32 v7, 19, v15
	v_cndmask_b32_e32 v6, v156, v231, vcc
	v_cmp_gt_i32_e32 vcc, v7, v233
	v_cmp_le_i32_e64 s[6:7], v7, v245
	s_or_b64 s[6:7], vcc, s[6:7]
	v_or_b32_e32 v9, 33, v15
	v_cndmask_b32_e64 v7, v157, v231, s[6:7]
	v_max3_f32 v10, v8, v6, v7
	v_or_b32_e32 v8, 32, v15
	v_cmp_gt_i32_e32 vcc, v8, v233
	v_cmp_le_i32_e64 s[8:9], v8, v245
	s_or_b64 vcc, vcc, s[8:9]
	v_cndmask_b32_e32 v8, v150, v231, vcc
	v_cmp_gt_i32_e32 vcc, v9, v233
	v_cmp_le_i32_e64 s[8:9], v9, v245
	s_or_b64 vcc, vcc, s[8:9]
	v_cndmask_b32_e32 v9, v151, v231, vcc
	v_max3_f32 v12, v10, v8, v9
	v_or_b32_e32 v10, 34, v15
	v_cmp_gt_i32_e32 vcc, v10, v233
	v_cmp_le_i32_e64 s[8:9], v10, v245
	s_or_b64 vcc, vcc, s[8:9]
	v_or_b32_e32 v11, 35, v15
	v_cndmask_b32_e32 v10, v152, v231, vcc
	v_cmp_gt_i32_e32 vcc, v11, v233
	v_cmp_le_i32_e64 s[8:9], v11, v245
	s_or_b64 s[8:9], vcc, s[8:9]
	v_or_b32_e32 v13, 49, v15
	v_cndmask_b32_e64 v11, v153, v231, s[8:9]
	v_max3_f32 v14, v12, v10, v11
	v_or_b32_e32 v12, 48, v15
	v_cmp_gt_i32_e32 vcc, v12, v233
	v_cmp_le_i32_e64 s[10:11], v12, v245
	s_or_b64 vcc, vcc, s[10:11]
	v_cndmask_b32_e32 v12, v146, v231, vcc
	v_cmp_gt_i32_e32 vcc, v13, v233
	v_cmp_le_i32_e64 s[10:11], v13, v245
	s_or_b64 vcc, vcc, s[10:11]
	v_cndmask_b32_e32 v13, v147, v231, vcc
	v_max3_f32 v162, v14, v12, v13
	v_or_b32_e32 v14, 50, v15
	v_cmp_gt_i32_e32 vcc, v14, v233
	v_cmp_le_i32_e64 s[10:11], v14, v245
	s_or_b64 vcc, vcc, s[10:11]
	v_or_b32_e32 v15, 51, v15
	v_cndmask_b32_e32 v14, v148, v231, vcc
	v_cmp_gt_i32_e32 vcc, v15, v233
	v_cmp_le_i32_e64 s[10:11], v15, v245
	s_or_b64 s[10:11], vcc, s[10:11]
	s_nop 0
	v_cndmask_b32_e64 v15, v149, v231, s[10:11]
	v_max3_f32 v162, v162, v14, v15
	v_mov_b32_e32 v163, v162
	s_nop 1
	v_permlane16_swap_b32_e32 v162, v163
	v_max_f32_e32 v163, v163, v163
	v_max_f32_e32 v162, v162, v162
	v_max_f32_e32 v162, v162, v163
	v_mov_b32_e32 v163, v162
	s_nop 1
	v_permlane32_swap_b32_e32 v162, v163
	v_max_f32_e32 v163, v163, v163
	v_max_f32_e32 v162, v162, v162
	v_max_f32_e32 v162, v162, v163
	v_cmp_gt_f32_e32 vcc, v162, v249
	s_cbranch_vccz .LBB0_847
	v_max_f32_e32 v7, v162, v162
	v_max_f32_e32 v11, v246, v246
	v_max_f32_e32 v248, v11, v7
	v_sub_f32_e32 v7, v246, v248
	v_mul_f32_e32 v7, 0x3e0293ee, v7
	v_exp_f32_e32 v190, v7
	v_cndmask_b32_e64 v3, v161, v231, s[4:5]
	v_cndmask_b32_e64 v7, v157, v231, s[6:7]
	v_cndmask_b32_e64 v11, v153, v231, s[8:9]
	v_cndmask_b32_e64 v15, v149, v231, s[10:11]
	v_mul_f32_e32 v250, v244, v190
	v_pk_mul_f32 v[164:165], v[128:129], v[190:191] op_sel_hi:[1,0]
	v_pk_mul_f32 v[162:163], v[126:127], v[190:191] op_sel_hi:[1,0]
	v_pk_mul_f32 v[168:169], v[124:125], v[190:191] op_sel_hi:[1,0]
	v_pk_mul_f32 v[166:167], v[122:123], v[190:191] op_sel_hi:[1,0]
	v_pk_mul_f32 v[172:173], v[120:121], v[190:191] op_sel_hi:[1,0]
	v_pk_mul_f32 v[170:171], v[118:119], v[190:191] op_sel_hi:[1,0]
	v_pk_mul_f32 v[176:177], v[116:117], v[190:191] op_sel_hi:[1,0]
	v_pk_mul_f32 v[174:175], v[114:115], v[190:191] op_sel_hi:[1,0]
	v_pk_mul_f32 v[180:181], v[112:113], v[190:191] op_sel_hi:[1,0]
	v_pk_mul_f32 v[178:179], v[110:111], v[190:191] op_sel_hi:[1,0]
	v_pk_mul_f32 v[184:185], v[108:109], v[190:191] op_sel_hi:[1,0]
	v_pk_mul_f32 v[182:183], v[106:107], v[190:191] op_sel_hi:[1,0]
	v_pk_mul_f32 v[188:189], v[104:105], v[190:191] op_sel_hi:[1,0]
	v_pk_mul_f32 v[186:187], v[102:103], v[190:191] op_sel_hi:[1,0]
	v_pk_mul_f32 v[192:193], v[100:101], v[190:191] op_sel_hi:[1,0]
	v_pk_mul_f32 v[190:191], v[98:99], v[190:191] op_sel_hi:[1,0]
	s_branch .LBB0_848
